# P6a gated epilogue: second half-tile's gate loads issued together with the first half's (one exposed round trip instead of two)
# baseline (speedup 1.0000x reference)
;     __device__ __forceinline__ void operator()(const pg8::f32x4 (&acc)[2][2][4][2], const pg8::Unit& u, int wr, int wc, int fr, int fq) const {
;     ...
;         for (int ai = 0; ai < 2; ++ai) {
;             v4u gq[4][2], aq[4][2];
;             if (GATE) {
; #pragma unroll
;                 for (int m = 0; m < 4; ++m)
; #pragma unroll
;                     for (int bj = 0; bj < 2; ++bj) gq[m][bj] = *(const v4u*)(G + (size_t)(row0 + ai * 128 + m * 16) * D + col0 + bj * 128);
;             }
;             if (ADD) {
; #pragma unroll
;                 for (int m = 0; m < 4; ++m)
; #pragma unroll
;                     for (int bj = 0; bj < 2; ++bj) aq[m][bj] = *(const v4u*)(A2 + (size_t)(row0 + ai * 128 + m * 16) * D + col0 + bj * 128);
;             }
; #pragma unroll
;             for (int m = 0; m < 4; ++m) {
;                 const int row = row0 + ai * 128 + m * 16;
;                 const size_t off = (size_t)row * D + col0;
;                 float s = 0.f;
; #pragma unroll
;                 for (int bj = 0; bj < 2; ++bj) {
;                     float r[8];
; #pragma unroll
;                     for (int j = 0; j < 4; ++j) { r[j] = acc[ai][bj][m][0][j]; r[4 + j] = acc[ai][bj][m][1][j]; }
;                     if (RSCALE) { const float rv = rvs[ai][m];
; #pragma unroll
;                         for (int j = 0; j < 8; ++j) r[j] *= rv; }
;                     if (ACT == 1) {
; #pragma unroll
;                         for (int j = 0; j < 8; ++j) r[j] = sigmoid_fast(r[j]);
;                     }
;                     if (GATE) { const v4u g = gq[m][bj];
;                         r[0] *= bf_lo(g.x); r[1] *= bf_hi(g.x); r[2] *= bf_lo(g.y); r[3] *= bf_hi(g.y); r[4] *= bf_lo(g.z); r[5] *= bf_hi(g.z); r[6] *= bf_lo(g.w); r[7] *= bf_hi(g.w); }
;                     if (ADD) { const v4u g = aq[m][bj];
;                         r[0] += bf_lo(g.x); r[1] += bf_hi(g.x); r[2] += bf_lo(g.y); r[3] += bf_hi(g.y); r[4] += bf_lo(g.z); r[5] += bf_hi(g.z); r[6] += bf_lo(g.w); r[7] += bf_hi(g.w); }
;                     if (PART) {
; #pragma unroll
;                         for (int j = 0; j < 8; ++j) s += r[j] * r[j];
;                     }
;                     v4u w; w.x = pk2(r[0], r[1]); w.y = pk2(r[2], r[3]); w.z = pk2(r[4], r[5]); w.w = pk2(r[6], r[7]);
;                     st16_wt(O + off + bj * 128, w);
.LBB0_790:
	v_lshl_add_u32 v142, s42, 8, v160
	v_lshl_or_b32 v136, s60, 8, v162
	v_ashrrev_i32_e32 v137, 31, v136
	v_or_b32_e32 v174, 16, v142
	v_lshlrev_b64 v[136:137], 1, v[136:137]
	v_ashrrev_i32_e32 v143, 31, v142
	v_ashrrev_i32_e32 v175, 31, v174
	v_lshl_add_u64 v[138:139], s[18:19], 0, v[136:137]
	v_lshlrev_b64 v[140:141], 11, v[142:143]
	v_lshlrev_b64 v[186:187], 11, v[174:175]
	v_lshl_add_u64 v[170:171], v[138:139], 0, v[140:141]
	v_lshl_add_u64 v[178:179], v[138:139], 0, v[186:187]
	global_load_dwordx4 v[166:169], v[170:171], off
	s_nop 0
	global_load_dwordx4 v[170:173], v[170:171], off offset:256
	s_nop 0
	global_load_dwordx4 v[174:177], v[178:179], off
	s_nop 0
	global_load_dwordx4 v[178:181], v[178:179], off offset:256
	v_or_b32_e32 v182, 32, v142
	v_ashrrev_i32_e32 v183, 31, v182
	v_lshlrev_b64 v[200:201], 11, v[182:183]
	v_lshl_add_u64 v[188:189], v[138:139], 0, v[200:201]
	global_load_dwordx4 v[182:185], v[188:189], off
	v_or_b32_e32 v142, 48, v142
	v_ashrrev_i32_e32 v143, 31, v142
	v_lshlrev_b64 v[142:143], 11, v[142:143]
	v_lshl_add_u64 v[190:191], s[26:27], 0, v[140:141]
	v_lshl_add_u64 v[196:197], v[138:139], 0, v[142:143]
	v_lshl_add_u64 v[202:203], v[190:191], 0, v[136:137]
	v_lshl_add_u64 v[204:205], s[26:27], 0, v[186:187]
	global_load_dwordx4 v[186:189], v[188:189], off offset:256
	s_nop 0
	global_load_dwordx4 v[190:193], v[196:197], off
	s_nop 0
	global_load_dwordx4 v[196:199], v[196:197], off offset:256
	v_lshl_add_u64 v[252:253], v[138:139], 0, v[140:141]
	v_add_co_u32_e32 v252, vcc, 0x40000, v252
	s_nop 1
	v_addc_co_u32_e32 v253, vcc, 0, v253, vcc
	global_load_dwordx4 v[220:223], v[252:253], off
	global_load_dwordx4 v[224:227], v[252:253], off offset:256
	v_add_co_u32_e32 v252, vcc, 0x8000, v252
	s_nop 1
	v_addc_co_u32_e32 v253, vcc, 0, v253, vcc
	global_load_dwordx4 v[228:231], v[252:253], off
	global_load_dwordx4 v[232:235], v[252:253], off offset:256
	v_add_co_u32_e32 v252, vcc, 0x8000, v252
	s_nop 1
	v_addc_co_u32_e32 v253, vcc, 0, v253, vcc
	global_load_dwordx4 v[236:239], v[252:253], off
	global_load_dwordx4 v[240:243], v[252:253], off offset:256
	v_add_co_u32_e32 v252, vcc, 0x8000, v252
	s_nop 1
	v_addc_co_u32_e32 v253, vcc, 0, v253, vcc
	global_load_dwordx4 v[244:247], v[252:253], off
	global_load_dwordx4 v[248:251], v[252:253], off offset:256
	v_lshl_add_u64 v[204:205], v[204:205], 0, v[136:137]
	s_mov_b64 s[44:45], 0x40000
	s_andn2_b64 vcc, exec, s[0:1]
	s_mov_b64 s[0:1], -1
	s_waitcnt vmcnt(0)
	v_lshlrev_b32_e32 v206, 16, v166
	v_and_b32_e32 v207, 0xffff0000, v166
	v_lshlrev_b32_e32 v166, 16, v167
	v_and_b32_e32 v167, 0xffff0000, v167
	v_lshlrev_b32_e32 v208, 16, v168
	v_and_b32_e32 v209, 0xffff0000, v168
	v_lshlrev_b32_e32 v168, 16, v169
	v_and_b32_e32 v169, 0xffff0000, v169
	v_lshlrev_b32_e32 v210, 16, v170
	v_and_b32_e32 v211, 0xffff0000, v170
	v_lshlrev_b32_e32 v170, 16, v171
	v_and_b32_e32 v171, 0xffff0000, v171
	v_lshlrev_b32_e32 v212, 16, v172
	v_and_b32_e32 v213, 0xffff0000, v172
	v_lshlrev_b32_e32 v172, 16, v173
	v_and_b32_e32 v173, 0xffff0000, v173
	v_lshlrev_b32_e32 v214, 16, v174
	v_and_b32_e32 v215, 0xffff0000, v174
	v_lshlrev_b32_e32 v174, 16, v175
	v_and_b32_e32 v175, 0xffff0000, v175
	v_lshlrev_b32_e32 v216, 16, v176
	v_and_b32_e32 v217, 0xffff0000, v176
	v_lshlrev_b32_e32 v176, 16, v177
	v_and_b32_e32 v177, 0xffff0000, v177
	v_lshlrev_b32_e32 v218, 16, v178
	v_and_b32_e32 v219, 0xffff0000, v178
	v_lshlrev_b32_e32 v178, 16, v179
	v_and_b32_e32 v179, 0xffff0000, v179
	v_pk_mul_f32 v[124:125], v[124:125], v[206:207]
	v_pk_mul_f32 v[126:127], v[126:127], v[166:167]
	v_pk_mul_f32 v[120:121], v[120:121], v[208:209]
	v_pk_mul_f32 v[122:123], v[122:123], v[168:169]
	v_pk_mul_f32 v[108:109], v[108:109], v[210:211]
	v_pk_mul_f32 v[110:111], v[110:111], v[170:171]
	v_pk_mul_f32 v[166:167], v[104:105], v[212:213]
	v_pk_mul_f32 v[168:169], v[106:107], v[172:173]
	v_pk_mul_f32 v[116:117], v[116:117], v[214:215]
	v_pk_mul_f32 v[118:119], v[118:119], v[174:175]
	v_pk_mul_f32 v[112:113], v[112:113], v[216:217]
	v_pk_mul_f32 v[114:115], v[114:115], v[176:177]
	v_pk_mul_f32 v[170:171], v[100:101], v[218:219]
	v_pk_mul_f32 v[172:173], v[102:103], v[178:179]
	v_cvt_pk_bf16_f32 v100, v124, v125
	v_cvt_pk_bf16_f32 v101, v126, v127
	v_cvt_pk_bf16_f32 v102, v120, v121
	v_cvt_pk_bf16_f32 v103, v122, v123
	v_cvt_pk_bf16_f32 v104, v108, v109
	v_cvt_pk_bf16_f32 v105, v110, v111
	v_cvt_pk_bf16_f32 v106, v166, v167
	v_cvt_pk_bf16_f32 v107, v168, v169
	v_cvt_pk_bf16_f32 v108, v116, v117
	v_cvt_pk_bf16_f32 v109, v118, v119
	v_cvt_pk_bf16_f32 v110, v112, v113
	v_cvt_pk_bf16_f32 v111, v114, v115
	global_store_dwordx4 v[202:203], v[100:103], off
	global_store_dwordx4 v[202:203], v[104:107], off offset:256
	global_store_dwordx4 v[204:205], v[108:111], off
	v_lshlrev_b32_e32 v100, 16, v180
	v_and_b32_e32 v101, 0xffff0000, v180
	v_pk_mul_f32 v[100:101], v[92:93], v[100:101]
	v_lshlrev_b32_e32 v92, 16, v181
	v_and_b32_e32 v93, 0xffff0000, v181
	v_pk_mul_f32 v[102:103], v[94:95], v[92:93]
	v_cvt_pk_bf16_f32 v92, v170, v171
	v_cvt_pk_bf16_f32 v93, v172, v173
	v_cvt_pk_bf16_f32 v94, v100, v101
	v_cvt_pk_bf16_f32 v95, v102, v103
	global_store_dwordx4 v[204:205], v[92:95], off offset:256
	v_lshl_add_u64 v[102:103], v[140:141], 0, s[14:15]
	s_nop 0
	v_lshlrev_b32_e32 v92, 16, v182
	v_and_b32_e32 v93, 0xffff0000, v182
	v_pk_mul_f32 v[92:93], v[96:97], v[92:93]
	v_lshlrev_b32_e32 v96, 16, v184
	v_and_b32_e32 v97, 0xffff0000, v184
	v_lshlrev_b32_e32 v94, 16, v183
	v_and_b32_e32 v95, 0xffff0000, v183
	v_pk_mul_f32 v[96:97], v[88:89], v[96:97]
	v_lshlrev_b32_e32 v88, 16, v185
	v_and_b32_e32 v89, 0xffff0000, v185
; __device__ __forceinline__ float bf_lo(unsigned w) { return __uint_as_float(w << 16); }
; __device__ __forceinline__ float bf_hi(unsigned w) { return __uint_as_float(w & 0xffff0000u); }
; __device__ __forceinline__ unsigned pk2(float lo, float hi) { bf16x2_t r = __builtin_convertvector((f32x2_t){lo, hi}, bf16x2_t); return __builtin_bit_cast(unsigned, r); }
; __device__ __forceinline__ float sigmoid_fast(float x) { return __builtin_amdgcn_rcpf(1.0f + __builtin_amdgcn_exp2f(-1.44269504089f * x)); }
;     __device__ __forceinline__ void operator()(const pg8::f32x4 (&acc)[2][2][4][2], const pg8::Unit& u, int wr, int wc, int fr, int fq) const {
;     ...
;             for (int m = 0; m < 4; ++m) {
;                 const int row = row0 + ai * 128 + m * 16;
;                 const size_t off = (size_t)row * D + col0;
;                 float s = 0.f;
; #pragma unroll
;                 for (int bj = 0; bj < 2; ++bj) {
;                     float r[8];
; #pragma unroll
;                     for (int j = 0; j < 4; ++j) { r[j] = acc[ai][bj][m][0][j]; r[4 + j] = acc[ai][bj][m][1][j]; }
;                     if (RSCALE) { const float rv = rvs[ai][m];
; #pragma unroll
;                         for (int j = 0; j < 8; ++j) r[j] *= rv; }
;                     if (ACT == 1) {
; #pragma unroll
;                         for (int j = 0; j < 8; ++j) r[j] = sigmoid_fast(r[j]);
;                     }
;                     if (GATE) { const v4u g = gq[m][bj];
;                         r[0] *= bf_lo(g.x); r[1] *= bf_hi(g.x); r[2] *= bf_lo(g.y); r[3] *= bf_hi(g.y); r[4] *= bf_lo(g.z); r[5] *= bf_hi(g.z); r[6] *= bf_lo(g.w); r[7] *= bf_hi(g.w); }
;                     if (ADD) { const v4u g = aq[m][bj];
;                         r[0] += bf_lo(g.x); r[1] += bf_hi(g.x); r[2] += bf_lo(g.y); r[3] += bf_hi(g.y); r[4] += bf_lo(g.z); r[5] += bf_hi(g.z); r[6] += bf_lo(g.w); r[7] += bf_hi(g.w); }
;                     if (PART) {
; #pragma unroll
;                         for (int j = 0; j < 8; ++j) s += r[j] * r[j];
;                     }
;                     v4u w; w.x = pk2(r[0], r[1]); w.y = pk2(r[2], r[3]); w.z = pk2(r[4], r[5]); w.w = pk2(r[6], r[7]);
;                     st16_wt(O + off + bj * 128, w);
	v_pk_mul_f32 v[94:95], v[98:99], v[94:95]
	v_pk_mul_f32 v[98:99], v[90:91], v[88:89]
	v_cvt_pk_bf16_f32 v88, v92, v93
	v_lshl_add_u64 v[92:93], s[26:27], 0, v[200:201]
	v_cvt_pk_bf16_f32 v89, v94, v95
	v_cvt_pk_bf16_f32 v90, v96, v97
	v_cvt_pk_bf16_f32 v91, v98, v99
	v_lshl_add_u64 v[92:93], v[92:93], 0, v[136:137]
	global_store_dwordx4 v[92:93], v[88:91], off
	v_lshl_add_u64 v[96:97], v[140:141], 0, s[44:45]
	s_mov_b64 s[44:45], 0x48000
	v_lshlrev_b32_e32 v88, 16, v186
	v_and_b32_e32 v89, 0xffff0000, v186
	v_pk_mul_f32 v[84:85], v[84:85], v[88:89]
	v_lshlrev_b32_e32 v88, 16, v187
	v_and_b32_e32 v89, 0xffff0000, v187
	v_pk_mul_f32 v[86:87], v[86:87], v[88:89]
	v_lshlrev_b32_e32 v88, 16, v188
	v_and_b32_e32 v89, 0xffff0000, v188
	v_pk_mul_f32 v[88:89], v[76:77], v[88:89]
	v_lshlrev_b32_e32 v76, 16, v189
	v_and_b32_e32 v77, 0xffff0000, v189
	v_pk_mul_f32 v[90:91], v[78:79], v[76:77]
	v_cvt_pk_bf16_f32 v76, v84, v85
	v_cvt_pk_bf16_f32 v77, v86, v87
	v_cvt_pk_bf16_f32 v78, v88, v89
	v_cvt_pk_bf16_f32 v79, v90, v91
	global_store_dwordx4 v[92:93], v[76:79], off offset:256
	v_lshl_add_u64 v[98:99], v[140:141], 0, s[44:45]
	s_mov_b64 s[44:45], 0x50000
	v_lshlrev_b32_e32 v76, 16, v190
	v_and_b32_e32 v77, 0xffff0000, v190
	v_pk_mul_f32 v[76:77], v[80:81], v[76:77]
	v_lshlrev_b32_e32 v80, 16, v192
	v_and_b32_e32 v81, 0xffff0000, v192
	v_lshlrev_b32_e32 v78, 16, v191
	v_and_b32_e32 v79, 0xffff0000, v191
	v_pk_mul_f32 v[80:81], v[72:73], v[80:81]
	v_lshlrev_b32_e32 v72, 16, v193
	v_and_b32_e32 v73, 0xffff0000, v193
	v_pk_mul_f32 v[78:79], v[82:83], v[78:79]
	v_pk_mul_f32 v[82:83], v[74:75], v[72:73]
	v_cvt_pk_bf16_f32 v72, v76, v77
	v_lshl_add_u64 v[76:77], s[26:27], 0, v[142:143]
	v_cvt_pk_bf16_f32 v73, v78, v79
	v_cvt_pk_bf16_f32 v74, v80, v81
	v_cvt_pk_bf16_f32 v75, v82, v83
	v_lshl_add_u64 v[76:77], v[76:77], 0, v[136:137]
	global_store_dwordx4 v[76:77], v[72:75], off
	v_lshl_add_u64 v[100:101], v[140:141], 0, s[44:45]
	s_nop 0
	v_lshlrev_b32_e32 v72, 16, v196
	v_and_b32_e32 v73, 0xffff0000, v196
	v_pk_mul_f32 v[68:69], v[68:69], v[72:73]
	v_lshlrev_b32_e32 v72, 16, v197
	v_and_b32_e32 v73, 0xffff0000, v197
	v_pk_mul_f32 v[70:71], v[70:71], v[72:73]
	v_lshlrev_b32_e32 v72, 16, v198
	v_and_b32_e32 v73, 0xffff0000, v198
	v_pk_mul_f32 v[72:73], v[64:65], v[72:73]
	v_lshlrev_b32_e32 v64, 16, v199
	v_and_b32_e32 v65, 0xffff0000, v199
	v_pk_mul_f32 v[74:75], v[66:67], v[64:65]
	v_cvt_pk_bf16_f32 v64, v68, v69
	v_cvt_pk_bf16_f32 v65, v70, v71
	v_cvt_pk_bf16_f32 v66, v72, v73
	v_cvt_pk_bf16_f32 v67, v74, v75
	global_store_dwordx4 v[76:77], v[64:67], off offset:256
	s_nop 1
	s_nop 0
	v_lshlrev_b32_e32 v104, 16, v220
	v_and_b32_e32 v105, 0xffff0000, v220
	v_lshlrev_b32_e32 v220, 16, v221
	v_and_b32_e32 v221, 0xffff0000, v221
	v_pk_mul_f32 v[62:63], v[62:63], v[220:221]
	v_lshlrev_b32_e32 v220, 16, v222
	v_and_b32_e32 v221, 0xffff0000, v222
	v_pk_mul_f32 v[60:61], v[60:61], v[104:105]
	v_pk_mul_f32 v[220:221], v[56:57], v[220:221]
	v_lshlrev_b32_e32 v56, 16, v223
	v_and_b32_e32 v57, 0xffff0000, v223
	v_pk_mul_f32 v[222:223], v[58:59], v[56:57]
	v_cvt_pk_bf16_f32 v56, v60, v61
	v_lshl_add_u64 v[60:61], s[26:27], 0, v[96:97]
	v_cvt_pk_bf16_f32 v57, v62, v63
	v_cvt_pk_bf16_f32 v58, v220, v221
	v_cvt_pk_bf16_f32 v59, v222, v223
	v_lshl_add_u64 v[60:61], v[60:61], 0, v[136:137]
	global_store_dwordx4 v[60:61], v[56:59], off
	s_nop 0
	v_lshlrev_b32_e32 v56, 16, v224
	v_and_b32_e32 v57, 0xffff0000, v224
	v_pk_mul_f32 v[52:53], v[52:53], v[56:57]
	v_lshlrev_b32_e32 v56, 16, v225
	v_and_b32_e32 v57, 0xffff0000, v225
	v_pk_mul_f32 v[54:55], v[54:55], v[56:57]
	v_lshlrev_b32_e32 v56, 16, v226
	v_and_b32_e32 v57, 0xffff0000, v226
	v_pk_mul_f32 v[56:57], v[44:45], v[56:57]
	v_lshlrev_b32_e32 v44, 16, v227
	v_and_b32_e32 v45, 0xffff0000, v227
	v_pk_mul_f32 v[58:59], v[46:47], v[44:45]
	v_cvt_pk_bf16_f32 v44, v52, v53
	v_cvt_pk_bf16_f32 v45, v54, v55
	v_cvt_pk_bf16_f32 v46, v56, v57
	v_cvt_pk_bf16_f32 v47, v58, v59
	global_store_dwordx4 v[60:61], v[44:47], off offset:256
	s_nop 0
	v_lshlrev_b32_e32 v44, 16, v228
	v_and_b32_e32 v45, 0xffff0000, v228
	v_pk_mul_f32 v[44:45], v[48:49], v[44:45]
; #define PG8_BAR __builtin_amdgcn_s_barrier()
; __device__ __forceinline__ float bf_lo(unsigned w) { return __uint_as_float(w << 16); }
; __device__ __forceinline__ float bf_hi(unsigned w) { return __uint_as_float(w & 0xffff0000u); }
; __device__ __forceinline__ float sigmoid_fast(float x) { return __builtin_amdgcn_rcpf(1.0f + __builtin_amdgcn_exp2f(-1.44269504089f * x)); }
;     ...
;         if constexpr (ALIGN_EPI) { if (wr == 1) PG8_BAR; }
;     __device__ __forceinline__ void operator()(const pg8::f32x4 (&acc)[2][2][4][2], const pg8::Unit& u, int wr, int wc, int fr, int fq) const {
;     ...
;             for (int m = 0; m < 4; ++m) {
;                 const int row = row0 + ai * 128 + m * 16;
;                 const size_t off = (size_t)row * D + col0;
;                 float s = 0.f;
; #pragma unroll
;                 for (int bj = 0; bj < 2; ++bj) {
;                     float r[8];
; #pragma unroll
;                     for (int j = 0; j < 4; ++j) { r[j] = acc[ai][bj][m][0][j]; r[4 + j] = acc[ai][bj][m][1][j]; }
;                     if (RSCALE) { const float rv = rvs[ai][m];
; #pragma unroll
;                         for (int j = 0; j < 8; ++j) r[j] *= rv; }
;                     if (ACT == 1) {
; #pragma unroll
;                         for (int j = 0; j < 8; ++j) r[j] = sigmoid_fast(r[j]);
;                     }
;                     if (GATE) { const v4u g = gq[m][bj];
;                         r[0] *= bf_lo(g.x); r[1] *= bf_hi(g.x); r[2] *= bf_lo(g.y); r[3] *= bf_hi(g.y); r[4] *= bf_lo(g.z); r[5] *= bf_hi(g.z); r[6] *= bf_lo(g.w); r[7] *= bf_hi(g.w); }
;                     if (ADD) { const v4u g = aq[m][bj];
;                         r[0] += bf_lo(g.x); r[1] += bf_hi(g.x); r[2] += bf_lo(g.y); r[3] += bf_hi(g.y); r[4] += bf_lo(g.z); r[5] += bf_hi(g.z); r[6] += bf_lo(g.w); r[7] += bf_hi(g.w); }
;                     if (PART) {
; #pragma unroll
;                         for (int j = 0; j < 8; ++j) s += r[j] * r[j];
;                     }
;                     v4u w; w.x = pk2(r[0], r[1]); w.y = pk2(r[2], r[3]); w.z = pk2(r[4], r[5]); w.w = pk2(r[6], r[7]);
;                     st16_wt(O + off + bj * 128, w);
;                 }
;                 if (PART) { s += __shfl_xor(s, 16); s += __shfl_xor(s, 32); st4_wt(part + (size_t)row * 16 + u.pn * 4 + wc, s); }
;             }
;             if (GATE || ADD) asm volatile("" ::: "memory");
	v_lshlrev_b32_e32 v48, 16, v230
	v_and_b32_e32 v49, 0xffff0000, v230
	v_lshlrev_b32_e32 v46, 16, v229
	v_and_b32_e32 v47, 0xffff0000, v229
	v_pk_mul_f32 v[48:49], v[40:41], v[48:49]
	v_lshlrev_b32_e32 v40, 16, v231
	v_and_b32_e32 v41, 0xffff0000, v231
	v_pk_mul_f32 v[46:47], v[50:51], v[46:47]
	v_pk_mul_f32 v[50:51], v[42:43], v[40:41]
	v_cvt_pk_bf16_f32 v40, v44, v45
	v_lshl_add_u64 v[44:45], s[26:27], 0, v[98:99]
	v_cvt_pk_bf16_f32 v41, v46, v47
	v_cvt_pk_bf16_f32 v42, v48, v49
	v_cvt_pk_bf16_f32 v43, v50, v51
	v_lshl_add_u64 v[44:45], v[44:45], 0, v[136:137]
	global_store_dwordx4 v[44:45], v[40:43], off
	s_nop 0
	v_lshlrev_b32_e32 v40, 16, v232
	v_and_b32_e32 v41, 0xffff0000, v232
	v_pk_mul_f32 v[36:37], v[36:37], v[40:41]
	v_lshlrev_b32_e32 v40, 16, v233
	v_and_b32_e32 v41, 0xffff0000, v233
	v_pk_mul_f32 v[38:39], v[38:39], v[40:41]
	v_lshlrev_b32_e32 v40, 16, v234
	v_and_b32_e32 v41, 0xffff0000, v234
	v_pk_mul_f32 v[40:41], v[28:29], v[40:41]
	v_lshlrev_b32_e32 v28, 16, v235
	v_and_b32_e32 v29, 0xffff0000, v235
	v_pk_mul_f32 v[42:43], v[30:31], v[28:29]
	v_cvt_pk_bf16_f32 v28, v36, v37
	v_cvt_pk_bf16_f32 v29, v38, v39
	v_cvt_pk_bf16_f32 v30, v40, v41
	v_cvt_pk_bf16_f32 v31, v42, v43
	global_store_dwordx4 v[44:45], v[28:31], off offset:256
	s_nop 0
	v_lshlrev_b32_e32 v28, 16, v236
	v_and_b32_e32 v29, 0xffff0000, v236
	v_pk_mul_f32 v[28:29], v[32:33], v[28:29]
	v_lshlrev_b32_e32 v32, 16, v238
	v_and_b32_e32 v33, 0xffff0000, v238
	v_lshlrev_b32_e32 v30, 16, v237
	v_and_b32_e32 v31, 0xffff0000, v237
	v_pk_mul_f32 v[32:33], v[24:25], v[32:33]
	v_lshlrev_b32_e32 v24, 16, v239
	v_and_b32_e32 v25, 0xffff0000, v239
	v_pk_mul_f32 v[30:31], v[34:35], v[30:31]
	v_pk_mul_f32 v[34:35], v[26:27], v[24:25]
	v_cvt_pk_bf16_f32 v24, v28, v29
	v_lshl_add_u64 v[28:29], s[26:27], 0, v[100:101]
	v_cvt_pk_bf16_f32 v25, v30, v31
	v_cvt_pk_bf16_f32 v26, v32, v33
	v_cvt_pk_bf16_f32 v27, v34, v35
	v_lshl_add_u64 v[28:29], v[28:29], 0, v[136:137]
	global_store_dwordx4 v[28:29], v[24:27], off
	s_nop 0
	v_lshlrev_b32_e32 v24, 16, v240
	v_and_b32_e32 v25, 0xffff0000, v240
	v_pk_mul_f32 v[20:21], v[20:21], v[24:25]
	v_lshlrev_b32_e32 v24, 16, v241
	v_and_b32_e32 v25, 0xffff0000, v241
	v_pk_mul_f32 v[22:23], v[22:23], v[24:25]
	v_lshlrev_b32_e32 v24, 16, v242
	v_and_b32_e32 v25, 0xffff0000, v242
	v_pk_mul_f32 v[24:25], v[12:13], v[24:25]
	v_lshlrev_b32_e32 v12, 16, v243
	v_and_b32_e32 v13, 0xffff0000, v243
	v_pk_mul_f32 v[26:27], v[14:15], v[12:13]
	v_cvt_pk_bf16_f32 v12, v20, v21
	v_cvt_pk_bf16_f32 v13, v22, v23
	v_cvt_pk_bf16_f32 v14, v24, v25
	v_cvt_pk_bf16_f32 v15, v26, v27
	global_store_dwordx4 v[28:29], v[12:15], off offset:256
	s_nop 0
	v_lshlrev_b32_e32 v12, 16, v244
	v_and_b32_e32 v13, 0xffff0000, v244
	v_pk_mul_f32 v[12:13], v[16:17], v[12:13]
	v_lshlrev_b32_e32 v16, 16, v246
	v_and_b32_e32 v17, 0xffff0000, v246
	v_lshlrev_b32_e32 v14, 16, v245
	v_and_b32_e32 v15, 0xffff0000, v245
	v_pk_mul_f32 v[16:17], v[8:9], v[16:17]
	v_lshlrev_b32_e32 v8, 16, v247
	v_and_b32_e32 v9, 0xffff0000, v247
	v_pk_mul_f32 v[14:15], v[18:19], v[14:15]
	v_pk_mul_f32 v[18:19], v[10:11], v[8:9]
	v_cvt_pk_bf16_f32 v8, v12, v13
	v_lshl_add_u64 v[12:13], s[26:27], 0, v[102:103]
	v_cvt_pk_bf16_f32 v9, v14, v15
	v_cvt_pk_bf16_f32 v10, v16, v17
	v_cvt_pk_bf16_f32 v11, v18, v19
	v_lshl_add_u64 v[12:13], v[12:13], 0, v[136:137]
	global_store_dwordx4 v[12:13], v[8:11], off
	s_nop 0
	v_lshlrev_b32_e32 v8, 16, v248
	v_and_b32_e32 v9, 0xffff0000, v248
	v_pk_mul_f32 v[4:5], v[4:5], v[8:9]
	v_lshlrev_b32_e32 v8, 16, v249
	v_and_b32_e32 v9, 0xffff0000, v249
	v_pk_mul_f32 v[6:7], v[6:7], v[8:9]
	v_lshlrev_b32_e32 v8, 16, v250
	v_and_b32_e32 v9, 0xffff0000, v250
	v_pk_mul_f32 v[8:9], v[0:1], v[8:9]
	v_lshlrev_b32_e32 v0, 16, v251
	v_and_b32_e32 v1, 0xffff0000, v251
	v_pk_mul_f32 v[10:11], v[2:3], v[0:1]
	v_cvt_pk_bf16_f32 v0, v4, v5
	v_cvt_pk_bf16_f32 v1, v6, v7
	v_cvt_pk_bf16_f32 v2, v8, v9
	v_cvt_pk_bf16_f32 v3, v10, v11
	global_store_dwordx4 v[12:13], v[0:3], off offset:256
	s_cbranch_vccnz .LBB0_779
	s_andn2_b64 vcc, exec, s[8:9]
	s_cbranch_vccnz .LBB0_778
	s_barrier
	s_branch .LBB0_778
